# GEMM main loops: loop-carried scalar updates and exit compare hoisted above the loop-back barrier (loop-edge edit)
# baseline (speedup 1.0000x reference)
.LBB0_174:
	s_add_u32 s22, s4, 0xfffc0080
	s_addc_u32 s23, s5, -1
	s_add_i32 s54, 0, 0x10000
	s_cmp_eq_u32 s53, 12
	s_cselect_b32 s25, s3, s23
	s_cselect_b32 s24, s17, s22
	v_add_u32_e32 v0, s54, v173
	s_cselect_b32 s23, s15, s52
	s_cselect_b32 s22, s50, s51
	s_add_i32 s56, 0, 0x14000
	ds_read_b128 v[130:133], v0
	ds_read_b128 v[134:137], v0 offset:1024
	ds_read_b128 v[138:141], v0 offset:2048
	ds_read_b128 v[142:145], v0 offset:3072
	v_add_u32_e32 v0, s56, v173
	ds_read_b128 v[146:149], v0
	ds_read_b128 v[174:177], v0 offset:1024
	ds_read_b128 v[180:183], v0 offset:2048
	ds_read_b128 v[184:187], v0 offset:3072
	v_lshl_add_u64 v[170:171], s[4:5], 0, v[166:167]
	s_add_i32 m0, s31, 0xc000
	ds_read_b128 v[188:191], v179
	ds_read_b128 v[192:195], v179 offset:1024
	ds_read_b128 v[196:199], v179 offset:2048
	ds_read_b128 v[200:203], v179 offset:3072
	ds_read_b128 v[204:207], v179 offset:4096
	ds_read_b128 v[208:211], v179 offset:5120
	ds_read_b128 v[212:215], v179 offset:6144
	ds_read_b128 v[242:245], v179 offset:7168
	global_load_lds_dwordx4 v[170:171], off
	v_lshl_add_u64 v[170:171], s[4:5], 0, v[168:169]
	s_add_i32 m0, s31, 0xe000
	s_nop 0
	global_load_lds_dwordx4 v[170:171], off
	s_waitcnt vmcnt(8)
	s_waitcnt lgkmcnt(0)
	s_barrier
	s_setprio 1
	s_waitcnt lgkmcnt(0)
	v_mfma_f32_16x16x32_bf16 v[78:81], v[130:133], v[188:191], v[78:81]
	v_mfma_f32_16x16x32_bf16 v[74:77], v[138:141], v[188:191], v[74:77]
	v_mfma_f32_16x16x32_bf16 v[70:73], v[130:133], v[196:199], v[70:73]
	v_mfma_f32_16x16x32_bf16 v[62:65], v[138:141], v[196:199], v[62:65]
	v_mfma_f32_16x16x32_bf16 v[54:57], v[130:133], v[204:207], v[54:57]
	v_mfma_f32_16x16x32_bf16 v[50:53], v[138:141], v[204:207], v[50:53]
	v_mfma_f32_16x16x32_bf16 v[42:45], v[130:133], v[212:215], v[42:45]
	v_mfma_f32_16x16x32_bf16 v[34:37], v[138:141], v[212:215], v[34:37]
	v_mfma_f32_16x16x32_bf16 v[78:81], v[134:137], v[192:195], v[78:81]
	v_mfma_f32_16x16x32_bf16 v[74:77], v[142:145], v[192:195], v[74:77]
	v_mfma_f32_16x16x32_bf16 v[70:73], v[134:137], v[200:203], v[70:73]
	v_mfma_f32_16x16x32_bf16 v[62:65], v[142:145], v[200:203], v[62:65]
	v_mfma_f32_16x16x32_bf16 v[54:57], v[134:137], v[208:211], v[54:57]
	v_mfma_f32_16x16x32_bf16 v[50:53], v[142:145], v[208:211], v[50:53]
	v_mfma_f32_16x16x32_bf16 v[42:45], v[134:137], v[242:245], v[42:45]
	v_mfma_f32_16x16x32_bf16 v[34:37], v[142:145], v[242:245], v[34:37]
	s_setprio 0
	s_setprio 1
	v_mfma_f32_16x16x32_bf16 v[126:129], v[146:149], v[188:191], v[126:129]
	v_mfma_f32_16x16x32_bf16 v[122:125], v[180:183], v[188:191], v[122:125]
	v_mfma_f32_16x16x32_bf16 v[118:121], v[146:149], v[196:199], v[118:121]
	v_mfma_f32_16x16x32_bf16 v[114:117], v[180:183], v[196:199], v[114:117]
	v_mfma_f32_16x16x32_bf16 v[110:113], v[146:149], v[204:207], v[110:113]
	v_mfma_f32_16x16x32_bf16 v[106:109], v[180:183], v[204:207], v[106:109]
	v_mfma_f32_16x16x32_bf16 v[102:105], v[146:149], v[212:215], v[102:105]
	v_mfma_f32_16x16x32_bf16 v[98:101], v[180:183], v[212:215], v[98:101]
	v_mfma_f32_16x16x32_bf16 v[126:129], v[174:177], v[192:195], v[126:129]
	v_mfma_f32_16x16x32_bf16 v[122:125], v[184:187], v[192:195], v[122:125]
	v_mfma_f32_16x16x32_bf16 v[118:121], v[174:177], v[200:203], v[118:121]
	v_mfma_f32_16x16x32_bf16 v[114:117], v[184:187], v[200:203], v[114:117]
	v_mfma_f32_16x16x32_bf16 v[110:113], v[174:177], v[208:211], v[110:113]
	v_mfma_f32_16x16x32_bf16 v[106:109], v[184:187], v[208:211], v[106:109]
	v_mfma_f32_16x16x32_bf16 v[102:105], v[174:177], v[242:245], v[102:105]
	v_mfma_f32_16x16x32_bf16 v[98:101], v[184:187], v[242:245], v[98:101]
	s_setprio 0
	s_barrier
	s_add_i32 s54, s54, s28
	v_lshl_add_u64 v[170:171], s[22:23], 0, v[154:155]
	s_mov_b32 m0, s54
	ds_read_b128 v[188:191], v179 offset:16384
	ds_read_b128 v[192:195], v179 offset:17408
	ds_read_b128 v[196:199], v179 offset:18432
	ds_read_b128 v[200:203], v179 offset:19456
	ds_read_b128 v[204:207], v179 offset:20480
	ds_read_b128 v[208:211], v179 offset:21504
	ds_read_b128 v[212:215], v179 offset:22528
	ds_read_b128 v[242:245], v179 offset:23552
	global_load_lds_dwordx4 v[170:171], off
	s_add_i32 m0, s54, 0x2000
	s_add_u32 s54, s22, 0x40000
	v_lshl_add_u64 v[226:227], s[22:23], 0, v[150:151]
	s_addc_u32 s55, s23, 0
	s_add_i32 s56, s56, s28
	global_load_lds_dwordx4 v[226:227], off
	v_lshl_add_u64 v[246:247], s[54:55], 0, v[154:155]
	s_mov_b32 m0, s56
	v_lshl_add_u64 v[228:229], s[24:25], 0, v[152:153]
	global_load_lds_dwordx4 v[246:247], off
	v_lshl_add_u64 v[246:247], s[54:55], 0, v[150:151]
	s_add_i32 m0, s56, 0x2000
	s_nop 0
	global_load_lds_dwordx4 v[246:247], off
	v_lshl_add_u64 v[246:247], s[24:25], 0, v[156:157]
	s_mov_b32 m0, s31
	s_nop 0
	global_load_lds_dwordx4 v[246:247], off
	s_mov_b32 m0, s34
	s_nop 0
	global_load_lds_dwordx4 v[228:229], off
	s_waitcnt vmcnt(8)
	s_waitcnt lgkmcnt(0)
	s_barrier
	s_setprio 1
	s_waitcnt lgkmcnt(0)
	v_mfma_f32_16x16x32_bf16 v[30:33], v[130:133], v[188:191], v[30:33]
	v_mfma_f32_16x16x32_bf16 v[26:29], v[138:141], v[188:191], v[26:29]
	v_mfma_f32_16x16x32_bf16 v[22:25], v[130:133], v[196:199], v[22:25]
	v_mfma_f32_16x16x32_bf16 v[18:21], v[138:141], v[196:199], v[18:21]
	v_mfma_f32_16x16x32_bf16 v[14:17], v[130:133], v[204:207], v[14:17]
	v_mfma_f32_16x16x32_bf16 v[10:13], v[138:141], v[204:207], v[10:13]
	v_mfma_f32_16x16x32_bf16 v[6:9], v[130:133], v[212:215], v[6:9]
	v_mfma_f32_16x16x32_bf16 v[2:5], v[138:141], v[212:215], v[2:5]
	v_mfma_f32_16x16x32_bf16 v[30:33], v[134:137], v[192:195], v[30:33]
	v_mfma_f32_16x16x32_bf16 v[26:29], v[142:145], v[192:195], v[26:29]
	v_mfma_f32_16x16x32_bf16 v[22:25], v[134:137], v[200:203], v[22:25]
	v_mfma_f32_16x16x32_bf16 v[18:21], v[142:145], v[200:203], v[18:21]
	v_mfma_f32_16x16x32_bf16 v[14:17], v[134:137], v[208:211], v[14:17]
	v_mfma_f32_16x16x32_bf16 v[10:13], v[142:145], v[208:211], v[10:13]
	v_mfma_f32_16x16x32_bf16 v[6:9], v[134:137], v[242:245], v[6:9]
	v_mfma_f32_16x16x32_bf16 v[2:5], v[142:145], v[242:245], v[2:5]
	s_setprio 0
	s_setprio 1
	v_mfma_f32_16x16x32_bf16 v[94:97], v[146:149], v[188:191], v[94:97]
	v_mfma_f32_16x16x32_bf16 v[90:93], v[180:183], v[188:191], v[90:93]
	v_mfma_f32_16x16x32_bf16 v[86:89], v[146:149], v[196:199], v[86:89]
	v_mfma_f32_16x16x32_bf16 v[82:85], v[180:183], v[196:199], v[82:85]
	v_mfma_f32_16x16x32_bf16 v[66:69], v[146:149], v[204:207], v[66:69]
	v_mfma_f32_16x16x32_bf16 v[58:61], v[180:183], v[204:207], v[58:61]
	v_mfma_f32_16x16x32_bf16 v[46:49], v[146:149], v[212:215], v[46:49]
	v_mfma_f32_16x16x32_bf16 v[38:41], v[180:183], v[212:215], v[38:41]
	v_mfma_f32_16x16x32_bf16 v[94:97], v[174:177], v[192:195], v[94:97]
	v_mfma_f32_16x16x32_bf16 v[90:93], v[184:187], v[192:195], v[90:93]
	v_mfma_f32_16x16x32_bf16 v[86:89], v[174:177], v[200:203], v[86:89]
	v_mfma_f32_16x16x32_bf16 v[82:85], v[184:187], v[200:203], v[82:85]
	v_mfma_f32_16x16x32_bf16 v[66:69], v[174:177], v[208:211], v[66:69]
	v_mfma_f32_16x16x32_bf16 v[58:61], v[184:187], v[208:211], v[58:61]
	v_mfma_f32_16x16x32_bf16 v[46:49], v[174:177], v[242:245], v[46:49]
	v_mfma_f32_16x16x32_bf16 v[38:41], v[184:187], v[242:245], v[38:41]
	s_setprio 0
	s_barrier
	s_add_i32 s54, 0, 0x18000
	v_add_u32_e32 v0, s54, v173
	s_add_i32 s55, 0, 0x1c000
	ds_read_b128 v[130:133], v0
	ds_read_b128 v[134:137], v0 offset:1024
	ds_read_b128 v[138:141], v0 offset:2048
	ds_read_b128 v[142:145], v0 offset:3072
	v_add_u32_e32 v0, s55, v173
	ds_read_b128 v[146:149], v0
	ds_read_b128 v[174:177], v0 offset:1024
	ds_read_b128 v[180:183], v0 offset:2048
	ds_read_b128 v[184:187], v0 offset:3072
	s_add_u32 s24, s24, 0x40000
	s_addc_u32 s25, s25, 0
	s_mov_b32 m0, s35
	v_lshl_add_u64 v[230:231], s[24:25], 0, v[156:157]
	ds_read_b128 v[188:191], v179 offset:32768
	ds_read_b128 v[192:195], v179 offset:33792
	ds_read_b128 v[196:199], v179 offset:34816
	ds_read_b128 v[200:203], v179 offset:35840
	ds_read_b128 v[204:207], v179 offset:36864
	ds_read_b128 v[208:211], v179 offset:37888
	ds_read_b128 v[212:215], v179 offset:38912
	ds_read_b128 v[242:245], v179 offset:39936
	global_load_lds_dwordx4 v[230:231], off
	v_lshl_add_u64 v[230:231], s[24:25], 0, v[152:153]
	s_mov_b32 m0, s36
	s_nop 0
	global_load_lds_dwordx4 v[230:231], off
	s_waitcnt vmcnt(8)
	s_waitcnt lgkmcnt(0)
	s_barrier
	s_setprio 1
	s_waitcnt lgkmcnt(0)
	v_mfma_f32_16x16x32_bf16 v[78:81], v[130:133], v[188:191], v[78:81]
	v_mfma_f32_16x16x32_bf16 v[74:77], v[138:141], v[188:191], v[74:77]
	v_mfma_f32_16x16x32_bf16 v[70:73], v[130:133], v[196:199], v[70:73]
	v_mfma_f32_16x16x32_bf16 v[62:65], v[138:141], v[196:199], v[62:65]
	v_mfma_f32_16x16x32_bf16 v[54:57], v[130:133], v[204:207], v[54:57]
	v_mfma_f32_16x16x32_bf16 v[50:53], v[138:141], v[204:207], v[50:53]
	v_mfma_f32_16x16x32_bf16 v[42:45], v[130:133], v[212:215], v[42:45]
	v_mfma_f32_16x16x32_bf16 v[34:37], v[138:141], v[212:215], v[34:37]
	v_mfma_f32_16x16x32_bf16 v[78:81], v[134:137], v[192:195], v[78:81]
	v_mfma_f32_16x16x32_bf16 v[74:77], v[142:145], v[192:195], v[74:77]
	v_mfma_f32_16x16x32_bf16 v[70:73], v[134:137], v[200:203], v[70:73]
	v_mfma_f32_16x16x32_bf16 v[62:65], v[142:145], v[200:203], v[62:65]
	v_mfma_f32_16x16x32_bf16 v[54:57], v[134:137], v[208:211], v[54:57]
	v_mfma_f32_16x16x32_bf16 v[50:53], v[142:145], v[208:211], v[50:53]
	v_mfma_f32_16x16x32_bf16 v[42:45], v[134:137], v[242:245], v[42:45]
	v_mfma_f32_16x16x32_bf16 v[34:37], v[142:145], v[242:245], v[34:37]
	s_setprio 0
	s_setprio 1
	v_mfma_f32_16x16x32_bf16 v[126:129], v[146:149], v[188:191], v[126:129]
	v_mfma_f32_16x16x32_bf16 v[122:125], v[180:183], v[188:191], v[122:125]
	v_mfma_f32_16x16x32_bf16 v[118:121], v[146:149], v[196:199], v[118:121]
	v_mfma_f32_16x16x32_bf16 v[114:117], v[180:183], v[196:199], v[114:117]
	v_mfma_f32_16x16x32_bf16 v[110:113], v[146:149], v[204:207], v[110:113]
	v_mfma_f32_16x16x32_bf16 v[106:109], v[180:183], v[204:207], v[106:109]
	v_mfma_f32_16x16x32_bf16 v[102:105], v[146:149], v[212:215], v[102:105]
	v_mfma_f32_16x16x32_bf16 v[98:101], v[180:183], v[212:215], v[98:101]
	v_mfma_f32_16x16x32_bf16 v[126:129], v[174:177], v[192:195], v[126:129]
	v_mfma_f32_16x16x32_bf16 v[122:125], v[184:187], v[192:195], v[122:125]
	v_mfma_f32_16x16x32_bf16 v[118:121], v[174:177], v[200:203], v[118:121]
	v_mfma_f32_16x16x32_bf16 v[114:117], v[184:187], v[200:203], v[114:117]
	v_mfma_f32_16x16x32_bf16 v[110:113], v[174:177], v[208:211], v[110:113]
	v_mfma_f32_16x16x32_bf16 v[106:109], v[184:187], v[208:211], v[106:109]
	v_mfma_f32_16x16x32_bf16 v[102:105], v[174:177], v[242:245], v[102:105]
	v_mfma_f32_16x16x32_bf16 v[98:101], v[184:187], v[242:245], v[98:101]
	s_setprio 0
	s_barrier
	s_add_i32 s24, s54, s28
	v_lshl_add_u64 v[170:171], v[170:171], 0, s[94:95]
	s_mov_b32 m0, s24
	ds_read_b128 v[188:191], v179 offset:49152
	ds_read_b128 v[192:195], v179 offset:50176
	ds_read_b128 v[196:199], v179 offset:51200
	ds_read_b128 v[200:203], v179 offset:52224
	ds_read_b128 v[204:207], v179 offset:53248
	ds_read_b128 v[208:211], v179 offset:54272
	ds_read_b128 v[212:215], v179 offset:55296
	ds_read_b128 v[242:245], v179 offset:56320
	global_load_lds_dwordx4 v[170:171], off
	s_add_i32 m0, s24, 0x2000
	s_add_u32 s22, s22, 0x40080
	v_lshl_add_u64 v[170:171], v[226:227], 0, s[94:95]
	s_addc_u32 s23, s23, 0
	s_add_i32 s24, s55, s28
	global_load_lds_dwordx4 v[170:171], off
	v_lshl_add_u64 v[170:171], s[22:23], 0, v[154:155]
	s_mov_b32 m0, s24
	s_nop 0
	global_load_lds_dwordx4 v[170:171], off
	v_lshl_add_u64 v[170:171], s[22:23], 0, v[150:151]
	s_add_i32 m0, s24, 0x2000
	s_nop 0
	global_load_lds_dwordx4 v[170:171], off
	v_lshl_add_u64 v[170:171], v[246:247], 0, s[94:95]
	s_mov_b32 m0, s46
	s_nop 0
	global_load_lds_dwordx4 v[170:171], off
	v_lshl_add_u64 v[170:171], v[228:229], 0, s[94:95]
	s_mov_b32 m0, s47
	s_nop 0
	global_load_lds_dwordx4 v[170:171], off
	s_waitcnt vmcnt(8)
	s_waitcnt lgkmcnt(0)
	s_barrier
	s_setprio 1
	s_waitcnt lgkmcnt(0)
	v_mfma_f32_16x16x32_bf16 v[30:33], v[130:133], v[188:191], v[30:33]
	v_mfma_f32_16x16x32_bf16 v[26:29], v[138:141], v[188:191], v[26:29]
	v_mfma_f32_16x16x32_bf16 v[22:25], v[130:133], v[196:199], v[22:25]
	v_mfma_f32_16x16x32_bf16 v[18:21], v[138:141], v[196:199], v[18:21]
	v_mfma_f32_16x16x32_bf16 v[14:17], v[130:133], v[204:207], v[14:17]
	v_mfma_f32_16x16x32_bf16 v[10:13], v[138:141], v[204:207], v[10:13]
	v_mfma_f32_16x16x32_bf16 v[6:9], v[130:133], v[212:215], v[6:9]
	v_mfma_f32_16x16x32_bf16 v[2:5], v[138:141], v[212:215], v[2:5]
	v_mfma_f32_16x16x32_bf16 v[30:33], v[134:137], v[192:195], v[30:33]
	v_mfma_f32_16x16x32_bf16 v[26:29], v[142:145], v[192:195], v[26:29]
	v_mfma_f32_16x16x32_bf16 v[22:25], v[134:137], v[200:203], v[22:25]
	v_mfma_f32_16x16x32_bf16 v[18:21], v[142:145], v[200:203], v[18:21]
	v_mfma_f32_16x16x32_bf16 v[14:17], v[134:137], v[208:211], v[14:17]
	v_mfma_f32_16x16x32_bf16 v[10:13], v[142:145], v[208:211], v[10:13]
	v_mfma_f32_16x16x32_bf16 v[6:9], v[134:137], v[242:245], v[6:9]
	v_mfma_f32_16x16x32_bf16 v[2:5], v[142:145], v[242:245], v[2:5]
	s_setprio 0
	s_setprio 1
	v_mfma_f32_16x16x32_bf16 v[94:97], v[146:149], v[188:191], v[94:97]
	v_mfma_f32_16x16x32_bf16 v[90:93], v[180:183], v[188:191], v[90:93]
	v_mfma_f32_16x16x32_bf16 v[86:89], v[146:149], v[196:199], v[86:89]
	v_mfma_f32_16x16x32_bf16 v[82:85], v[180:183], v[196:199], v[82:85]
	v_mfma_f32_16x16x32_bf16 v[66:69], v[146:149], v[204:207], v[66:69]
	v_mfma_f32_16x16x32_bf16 v[58:61], v[180:183], v[204:207], v[58:61]
	v_mfma_f32_16x16x32_bf16 v[46:49], v[146:149], v[212:215], v[46:49]
	v_mfma_f32_16x16x32_bf16 v[38:41], v[180:183], v[212:215], v[38:41]
	v_mfma_f32_16x16x32_bf16 v[94:97], v[174:177], v[192:195], v[94:97]
	v_mfma_f32_16x16x32_bf16 v[90:93], v[184:187], v[192:195], v[90:93]
	v_mfma_f32_16x16x32_bf16 v[86:89], v[174:177], v[200:203], v[86:89]
	v_mfma_f32_16x16x32_bf16 v[82:85], v[184:187], v[200:203], v[82:85]
	v_mfma_f32_16x16x32_bf16 v[66:69], v[174:177], v[208:211], v[66:69]
	v_mfma_f32_16x16x32_bf16 v[58:61], v[184:187], v[208:211], v[58:61]
	v_mfma_f32_16x16x32_bf16 v[46:49], v[174:177], v[242:245], v[46:49]
	v_mfma_f32_16x16x32_bf16 v[38:41], v[184:187], v[242:245], v[38:41]
	s_add_i32 s53, s53, 2
	s_add_u32 s4, s4, 0x100
	s_addc_u32 s5, s5, 0
	s_add_u32 s51, s51, 0x100
	s_addc_u32 s52, s52, 0
	s_cmp_gt_u32 s53, 13
	s_setprio 0
	s_barrier
	s_cbranch_scc0 .LBB0_174
	s_and_b64 vcc, exec, s[10:11]
	s_cbranch_vccz .LBB0_177
	s_barrier

.LBB0_212:
	s_add_u32 s20, s18, 0xfffc0080
	s_addc_u32 s21, s19, -1
	s_add_i32 s41, 0, 0x10000
	s_cmp_eq_u32 s40, 12
	s_cselect_b32 s23, s13, s21
	s_cselect_b32 s22, s36, s20
	v_add_u32_e32 v142, s41, v145
	s_cselect_b32 s21, s11, s39
	s_cselect_b32 s20, s37, s38
	s_add_i32 s44, 0, 0x14000
	ds_read_b128 v[150:153], v142
	ds_read_b128 v[154:157], v142 offset:1024
	ds_read_b128 v[164:167], v142 offset:2048
	ds_read_b128 v[168:171], v142 offset:3072
	v_add_u32_e32 v142, s44, v145
	ds_read_b128 v[172:175], v142
	ds_read_b128 v[176:179], v142 offset:1024
	ds_read_b128 v[180:183], v142 offset:2048
	ds_read_b128 v[184:187], v142 offset:3072
	v_lshl_add_u64 v[146:147], s[18:19], 0, v[138:139]
	s_add_i32 m0, s25, 0xc000
	ds_read_b128 v[188:191], v149
	ds_read_b128 v[192:195], v149 offset:1024
	ds_read_b128 v[196:199], v149 offset:2048
	ds_read_b128 v[200:203], v149 offset:3072
	ds_read_b128 v[204:207], v149 offset:4096
	ds_read_b128 v[208:211], v149 offset:5120
	ds_read_b128 v[212:215], v149 offset:6144
	ds_read_b128 v[242:245], v149 offset:7168
	global_load_lds_dwordx4 v[146:147], off
	v_lshl_add_u64 v[146:147], s[18:19], 0, v[140:141]
	s_add_i32 m0, s25, 0xe000
	s_nop 0
	global_load_lds_dwordx4 v[146:147], off
	s_waitcnt vmcnt(8)
	s_waitcnt lgkmcnt(0)
	s_barrier
	s_setprio 1
	s_waitcnt lgkmcnt(0)
	v_mfma_f32_16x16x32_bf16 v[126:129], v[150:153], v[188:191], v[126:129]
	v_mfma_f32_16x16x32_bf16 v[122:125], v[164:167], v[188:191], v[122:125]
	v_mfma_f32_16x16x32_bf16 v[114:117], v[150:153], v[196:199], v[114:117]
	v_mfma_f32_16x16x32_bf16 v[106:109], v[164:167], v[196:199], v[106:109]
	v_mfma_f32_16x16x32_bf16 v[98:101], v[150:153], v[204:207], v[98:101]
	v_mfma_f32_16x16x32_bf16 v[90:93], v[164:167], v[204:207], v[90:93]
	v_mfma_f32_16x16x32_bf16 v[82:85], v[150:153], v[212:215], v[82:85]
	v_mfma_f32_16x16x32_bf16 v[74:77], v[164:167], v[212:215], v[74:77]
	v_mfma_f32_16x16x32_bf16 v[126:129], v[154:157], v[192:195], v[126:129]
	v_mfma_f32_16x16x32_bf16 v[122:125], v[168:171], v[192:195], v[122:125]
	v_mfma_f32_16x16x32_bf16 v[114:117], v[154:157], v[200:203], v[114:117]
	v_mfma_f32_16x16x32_bf16 v[106:109], v[168:171], v[200:203], v[106:109]
	v_mfma_f32_16x16x32_bf16 v[98:101], v[154:157], v[208:211], v[98:101]
	v_mfma_f32_16x16x32_bf16 v[90:93], v[168:171], v[208:211], v[90:93]
	v_mfma_f32_16x16x32_bf16 v[82:85], v[154:157], v[242:245], v[82:85]
	v_mfma_f32_16x16x32_bf16 v[74:77], v[168:171], v[242:245], v[74:77]
	s_setprio 0
	s_setprio 1
	v_mfma_f32_16x16x32_bf16 v[118:121], v[172:175], v[188:191], v[118:121]
	v_mfma_f32_16x16x32_bf16 v[110:113], v[180:183], v[188:191], v[110:113]
	v_mfma_f32_16x16x32_bf16 v[102:105], v[172:175], v[196:199], v[102:105]
	v_mfma_f32_16x16x32_bf16 v[94:97], v[180:183], v[196:199], v[94:97]
	v_mfma_f32_16x16x32_bf16 v[86:89], v[172:175], v[204:207], v[86:89]
	v_mfma_f32_16x16x32_bf16 v[78:81], v[180:183], v[204:207], v[78:81]
	v_mfma_f32_16x16x32_bf16 v[70:73], v[172:175], v[212:215], v[70:73]
	v_mfma_f32_16x16x32_bf16 v[66:69], v[180:183], v[212:215], v[66:69]
	v_mfma_f32_16x16x32_bf16 v[118:121], v[176:179], v[192:195], v[118:121]
	v_mfma_f32_16x16x32_bf16 v[110:113], v[184:187], v[192:195], v[110:113]
	v_mfma_f32_16x16x32_bf16 v[102:105], v[176:179], v[200:203], v[102:105]
	v_mfma_f32_16x16x32_bf16 v[94:97], v[184:187], v[200:203], v[94:97]
	v_mfma_f32_16x16x32_bf16 v[86:89], v[176:179], v[208:211], v[86:89]
	v_mfma_f32_16x16x32_bf16 v[78:81], v[184:187], v[208:211], v[78:81]
	v_mfma_f32_16x16x32_bf16 v[70:73], v[176:179], v[242:245], v[70:73]
	v_mfma_f32_16x16x32_bf16 v[66:69], v[184:187], v[242:245], v[66:69]
	s_setprio 0
	s_barrier
	s_add_i32 s41, s41, s24
	v_lshl_add_u64 v[146:147], s[20:21], 0, v[134:135]
	s_mov_b32 m0, s41
	ds_read_b128 v[188:191], v149 offset:16384
	ds_read_b128 v[192:195], v149 offset:17408
	ds_read_b128 v[196:199], v149 offset:18432
	ds_read_b128 v[200:203], v149 offset:19456
	ds_read_b128 v[204:207], v149 offset:20480
	ds_read_b128 v[208:211], v149 offset:21504
	ds_read_b128 v[212:215], v149 offset:22528
	ds_read_b128 v[242:245], v149 offset:23552
	global_load_lds_dwordx4 v[146:147], off
	s_add_i32 m0, s41, 0x2000
	s_add_u32 s42, s20, 0x40000
	v_lshl_add_u64 v[158:159], s[20:21], 0, v[130:131]
	s_addc_u32 s43, s21, 0
	s_add_i32 s41, s44, s24
	global_load_lds_dwordx4 v[158:159], off
	v_lshl_add_u64 v[226:227], s[42:43], 0, v[134:135]
	s_mov_b32 m0, s41
	v_lshl_add_u64 v[228:229], s[22:23], 0, v[132:133]
	global_load_lds_dwordx4 v[226:227], off
	v_lshl_add_u64 v[226:227], s[42:43], 0, v[130:131]
	s_add_i32 m0, s41, 0x2000
	s_nop 0
	global_load_lds_dwordx4 v[226:227], off
	v_lshl_add_u64 v[226:227], s[22:23], 0, v[136:137]
	s_mov_b32 m0, s25
	s_nop 0
	global_load_lds_dwordx4 v[226:227], off
	s_mov_b32 m0, s26
	s_nop 0
	global_load_lds_dwordx4 v[228:229], off
	s_waitcnt vmcnt(8)
	s_waitcnt lgkmcnt(0)
	s_barrier
	s_setprio 1
	s_waitcnt lgkmcnt(0)
	v_mfma_f32_16x16x32_bf16 v[62:65], v[150:153], v[188:191], v[62:65]
	v_mfma_f32_16x16x32_bf16 v[58:61], v[164:167], v[188:191], v[58:61]
	v_mfma_f32_16x16x32_bf16 v[50:53], v[150:153], v[196:199], v[50:53]
	v_mfma_f32_16x16x32_bf16 v[42:45], v[164:167], v[196:199], v[42:45]
	v_mfma_f32_16x16x32_bf16 v[34:37], v[150:153], v[204:207], v[34:37]
	v_mfma_f32_16x16x32_bf16 v[26:29], v[164:167], v[204:207], v[26:29]
	v_mfma_f32_16x16x32_bf16 v[18:21], v[150:153], v[212:215], v[18:21]
	v_mfma_f32_16x16x32_bf16 v[10:13], v[164:167], v[212:215], v[10:13]
	v_mfma_f32_16x16x32_bf16 v[62:65], v[154:157], v[192:195], v[62:65]
	v_mfma_f32_16x16x32_bf16 v[58:61], v[168:171], v[192:195], v[58:61]
	v_mfma_f32_16x16x32_bf16 v[50:53], v[154:157], v[200:203], v[50:53]
	v_mfma_f32_16x16x32_bf16 v[42:45], v[168:171], v[200:203], v[42:45]
	v_mfma_f32_16x16x32_bf16 v[34:37], v[154:157], v[208:211], v[34:37]
	v_mfma_f32_16x16x32_bf16 v[26:29], v[168:171], v[208:211], v[26:29]
	v_mfma_f32_16x16x32_bf16 v[18:21], v[154:157], v[242:245], v[18:21]
	v_mfma_f32_16x16x32_bf16 v[10:13], v[168:171], v[242:245], v[10:13]
	s_setprio 0
	s_setprio 1
	v_mfma_f32_16x16x32_bf16 v[54:57], v[172:175], v[188:191], v[54:57]
	v_mfma_f32_16x16x32_bf16 v[46:49], v[180:183], v[188:191], v[46:49]
	v_mfma_f32_16x16x32_bf16 v[38:41], v[172:175], v[196:199], v[38:41]
	v_mfma_f32_16x16x32_bf16 v[30:33], v[180:183], v[196:199], v[30:33]
	v_mfma_f32_16x16x32_bf16 v[22:25], v[172:175], v[204:207], v[22:25]
	v_mfma_f32_16x16x32_bf16 v[14:17], v[180:183], v[204:207], v[14:17]
	v_mfma_f32_16x16x32_bf16 v[6:9], v[172:175], v[212:215], v[6:9]
	v_mfma_f32_16x16x32_bf16 v[2:5], v[180:183], v[212:215], v[2:5]
	v_mfma_f32_16x16x32_bf16 v[54:57], v[176:179], v[192:195], v[54:57]
	v_mfma_f32_16x16x32_bf16 v[46:49], v[184:187], v[192:195], v[46:49]
	v_mfma_f32_16x16x32_bf16 v[38:41], v[176:179], v[200:203], v[38:41]
	v_mfma_f32_16x16x32_bf16 v[30:33], v[184:187], v[200:203], v[30:33]
	v_mfma_f32_16x16x32_bf16 v[22:25], v[176:179], v[208:211], v[22:25]
	v_mfma_f32_16x16x32_bf16 v[14:17], v[184:187], v[208:211], v[14:17]
	v_mfma_f32_16x16x32_bf16 v[6:9], v[176:179], v[242:245], v[6:9]
	v_mfma_f32_16x16x32_bf16 v[2:5], v[184:187], v[242:245], v[2:5]
	s_setprio 0
	s_barrier
	s_add_i32 s41, 0, 0x18000
	v_add_u32_e32 v142, s41, v145
	s_add_i32 s42, 0, 0x1c000
	ds_read_b128 v[150:153], v142
	ds_read_b128 v[154:157], v142 offset:1024
	ds_read_b128 v[164:167], v142 offset:2048
	ds_read_b128 v[168:171], v142 offset:3072
	v_add_u32_e32 v142, s42, v145
	ds_read_b128 v[172:175], v142
	ds_read_b128 v[176:179], v142 offset:1024
	ds_read_b128 v[180:183], v142 offset:2048
	ds_read_b128 v[184:187], v142 offset:3072
	s_add_u32 s22, s22, 0x40000
	s_addc_u32 s23, s23, 0
	s_mov_b32 m0, s27
	v_lshl_add_u64 v[230:231], s[22:23], 0, v[136:137]
	ds_read_b128 v[188:191], v149 offset:32768
	ds_read_b128 v[192:195], v149 offset:33792
	ds_read_b128 v[196:199], v149 offset:34816
	ds_read_b128 v[200:203], v149 offset:35840
	ds_read_b128 v[204:207], v149 offset:36864
	ds_read_b128 v[208:211], v149 offset:37888
	ds_read_b128 v[212:215], v149 offset:38912
	ds_read_b128 v[242:245], v149 offset:39936
	global_load_lds_dwordx4 v[230:231], off
	v_lshl_add_u64 v[230:231], s[22:23], 0, v[132:133]
	s_mov_b32 m0, s28
	s_nop 0
	global_load_lds_dwordx4 v[230:231], off
	s_waitcnt vmcnt(8)
	s_waitcnt lgkmcnt(0)
	s_barrier
	s_setprio 1
	s_waitcnt lgkmcnt(0)
	v_mfma_f32_16x16x32_bf16 v[126:129], v[150:153], v[188:191], v[126:129]
	v_mfma_f32_16x16x32_bf16 v[122:125], v[164:167], v[188:191], v[122:125]
	v_mfma_f32_16x16x32_bf16 v[114:117], v[150:153], v[196:199], v[114:117]
	v_mfma_f32_16x16x32_bf16 v[106:109], v[164:167], v[196:199], v[106:109]
	v_mfma_f32_16x16x32_bf16 v[98:101], v[150:153], v[204:207], v[98:101]
	v_mfma_f32_16x16x32_bf16 v[90:93], v[164:167], v[204:207], v[90:93]
	v_mfma_f32_16x16x32_bf16 v[82:85], v[150:153], v[212:215], v[82:85]
	v_mfma_f32_16x16x32_bf16 v[74:77], v[164:167], v[212:215], v[74:77]
	v_mfma_f32_16x16x32_bf16 v[126:129], v[154:157], v[192:195], v[126:129]
	v_mfma_f32_16x16x32_bf16 v[122:125], v[168:171], v[192:195], v[122:125]
	v_mfma_f32_16x16x32_bf16 v[114:117], v[154:157], v[200:203], v[114:117]
	v_mfma_f32_16x16x32_bf16 v[106:109], v[168:171], v[200:203], v[106:109]
	v_mfma_f32_16x16x32_bf16 v[98:101], v[154:157], v[208:211], v[98:101]
	v_mfma_f32_16x16x32_bf16 v[90:93], v[168:171], v[208:211], v[90:93]
	v_mfma_f32_16x16x32_bf16 v[82:85], v[154:157], v[242:245], v[82:85]
	v_mfma_f32_16x16x32_bf16 v[74:77], v[168:171], v[242:245], v[74:77]
	s_setprio 0
	s_setprio 1
	v_mfma_f32_16x16x32_bf16 v[118:121], v[172:175], v[188:191], v[118:121]
	v_mfma_f32_16x16x32_bf16 v[110:113], v[180:183], v[188:191], v[110:113]
	v_mfma_f32_16x16x32_bf16 v[102:105], v[172:175], v[196:199], v[102:105]
	v_mfma_f32_16x16x32_bf16 v[94:97], v[180:183], v[196:199], v[94:97]
	v_mfma_f32_16x16x32_bf16 v[86:89], v[172:175], v[204:207], v[86:89]
	v_mfma_f32_16x16x32_bf16 v[78:81], v[180:183], v[204:207], v[78:81]
	v_mfma_f32_16x16x32_bf16 v[70:73], v[172:175], v[212:215], v[70:73]
	v_mfma_f32_16x16x32_bf16 v[66:69], v[180:183], v[212:215], v[66:69]
	v_mfma_f32_16x16x32_bf16 v[118:121], v[176:179], v[192:195], v[118:121]
	v_mfma_f32_16x16x32_bf16 v[110:113], v[184:187], v[192:195], v[110:113]
	v_mfma_f32_16x16x32_bf16 v[102:105], v[176:179], v[200:203], v[102:105]
	v_mfma_f32_16x16x32_bf16 v[94:97], v[184:187], v[200:203], v[94:97]
	v_mfma_f32_16x16x32_bf16 v[86:89], v[176:179], v[208:211], v[86:89]
	v_mfma_f32_16x16x32_bf16 v[78:81], v[184:187], v[208:211], v[78:81]
	v_mfma_f32_16x16x32_bf16 v[70:73], v[176:179], v[242:245], v[70:73]
	v_mfma_f32_16x16x32_bf16 v[66:69], v[184:187], v[242:245], v[66:69]
	s_setprio 0
	s_barrier
	s_add_i32 s22, s41, s24
	v_lshl_add_u64 v[146:147], v[146:147], 0, s[94:95]
	s_mov_b32 m0, s22
	ds_read_b128 v[188:191], v149 offset:49152
	ds_read_b128 v[192:195], v149 offset:50176
	ds_read_b128 v[196:199], v149 offset:51200
	ds_read_b128 v[200:203], v149 offset:52224
	ds_read_b128 v[204:207], v149 offset:53248
	ds_read_b128 v[208:211], v149 offset:54272
	ds_read_b128 v[212:215], v149 offset:55296
	ds_read_b128 v[242:245], v149 offset:56320
	global_load_lds_dwordx4 v[146:147], off
	s_add_i32 m0, s22, 0x2000
	s_add_u32 s20, s20, 0x40080
	v_lshl_add_u64 v[146:147], v[158:159], 0, s[94:95]
	s_addc_u32 s21, s21, 0
	s_add_i32 s22, s42, s24
	global_load_lds_dwordx4 v[146:147], off
	v_lshl_add_u64 v[146:147], s[20:21], 0, v[134:135]
	s_mov_b32 m0, s22
	s_nop 0
	global_load_lds_dwordx4 v[146:147], off
	v_lshl_add_u64 v[146:147], s[20:21], 0, v[130:131]
	s_add_i32 m0, s22, 0x2000
	s_nop 0
	global_load_lds_dwordx4 v[146:147], off
	v_lshl_add_u64 v[146:147], v[226:227], 0, s[94:95]
	s_mov_b32 m0, s29
	s_nop 0
	global_load_lds_dwordx4 v[146:147], off
	v_lshl_add_u64 v[146:147], v[228:229], 0, s[94:95]
	s_mov_b32 m0, s30
	s_nop 0
	global_load_lds_dwordx4 v[146:147], off
	s_waitcnt vmcnt(8)
	s_waitcnt lgkmcnt(0)
	s_barrier
	s_setprio 1
	s_waitcnt lgkmcnt(0)
	v_mfma_f32_16x16x32_bf16 v[62:65], v[150:153], v[188:191], v[62:65]
	v_mfma_f32_16x16x32_bf16 v[58:61], v[164:167], v[188:191], v[58:61]
	v_mfma_f32_16x16x32_bf16 v[50:53], v[150:153], v[196:199], v[50:53]
	v_mfma_f32_16x16x32_bf16 v[42:45], v[164:167], v[196:199], v[42:45]
	v_mfma_f32_16x16x32_bf16 v[34:37], v[150:153], v[204:207], v[34:37]
	v_mfma_f32_16x16x32_bf16 v[26:29], v[164:167], v[204:207], v[26:29]
	v_mfma_f32_16x16x32_bf16 v[18:21], v[150:153], v[212:215], v[18:21]
	v_mfma_f32_16x16x32_bf16 v[10:13], v[164:167], v[212:215], v[10:13]
	v_mfma_f32_16x16x32_bf16 v[62:65], v[154:157], v[192:195], v[62:65]
	v_mfma_f32_16x16x32_bf16 v[58:61], v[168:171], v[192:195], v[58:61]
	v_mfma_f32_16x16x32_bf16 v[50:53], v[154:157], v[200:203], v[50:53]
	v_mfma_f32_16x16x32_bf16 v[42:45], v[168:171], v[200:203], v[42:45]
	v_mfma_f32_16x16x32_bf16 v[34:37], v[154:157], v[208:211], v[34:37]
	v_mfma_f32_16x16x32_bf16 v[26:29], v[168:171], v[208:211], v[26:29]
	v_mfma_f32_16x16x32_bf16 v[18:21], v[154:157], v[242:245], v[18:21]
	v_mfma_f32_16x16x32_bf16 v[10:13], v[168:171], v[242:245], v[10:13]
	s_setprio 0
	s_setprio 1
	v_mfma_f32_16x16x32_bf16 v[54:57], v[172:175], v[188:191], v[54:57]
	v_mfma_f32_16x16x32_bf16 v[46:49], v[180:183], v[188:191], v[46:49]
	v_mfma_f32_16x16x32_bf16 v[38:41], v[172:175], v[196:199], v[38:41]
	v_mfma_f32_16x16x32_bf16 v[30:33], v[180:183], v[196:199], v[30:33]
	v_mfma_f32_16x16x32_bf16 v[22:25], v[172:175], v[204:207], v[22:25]
	v_mfma_f32_16x16x32_bf16 v[14:17], v[180:183], v[204:207], v[14:17]
	v_mfma_f32_16x16x32_bf16 v[6:9], v[172:175], v[212:215], v[6:9]
	v_mfma_f32_16x16x32_bf16 v[2:5], v[180:183], v[212:215], v[2:5]
	v_mfma_f32_16x16x32_bf16 v[54:57], v[176:179], v[192:195], v[54:57]
	v_mfma_f32_16x16x32_bf16 v[46:49], v[184:187], v[192:195], v[46:49]
	v_mfma_f32_16x16x32_bf16 v[38:41], v[176:179], v[200:203], v[38:41]
	v_mfma_f32_16x16x32_bf16 v[30:33], v[184:187], v[200:203], v[30:33]
	v_mfma_f32_16x16x32_bf16 v[22:25], v[176:179], v[208:211], v[22:25]
	v_mfma_f32_16x16x32_bf16 v[14:17], v[184:187], v[208:211], v[14:17]
	v_mfma_f32_16x16x32_bf16 v[6:9], v[176:179], v[242:245], v[6:9]
	v_mfma_f32_16x16x32_bf16 v[2:5], v[184:187], v[242:245], v[2:5]
	s_add_i32 s40, s40, 2
	s_add_u32 s18, s18, 0x100
	s_addc_u32 s19, s19, 0
	s_add_u32 s38, s38, 0x100
	s_addc_u32 s39, s39, 0
	s_cmp_gt_u32 s40, 13
	s_setprio 0
	s_barrier
	s_cbranch_scc0 .LBB0_212
	v_readlane_b32 s40, v254, 38
	s_and_b64 vcc, exec, s[8:9]
	v_readlane_b32 s36, v254, 2
	v_readlane_b32 s41, v254, 39
	v_readlane_b32 s42, v254, 40
	v_readlane_b32 s43, v254, 41
	v_readlane_b32 s37, v254, 3
	s_cbranch_vccz .LBB0_215
	s_barrier

.LBB0_233:
	s_add_i32 s49, s24, 2
	s_add_u32 s50, s22, 0x80
	s_addc_u32 s25, s23, 0
	s_add_i32 s52, 0, 0x10000
	s_cmp_eq_u32 s42, s24
	s_cselect_b32 s25, s17, s25
	s_cselect_b32 s24, s45, s50
	v_add_u32_e32 v0, s52, v157
	s_cselect_b32 s51, s15, s48
	s_cselect_b32 s50, s46, s47
	s_add_i32 s53, 0, 0x14000
	ds_read_b128 v[126:129], v0
	ds_read_b128 v[134:137], v0 offset:1024
	ds_read_b128 v[138:141], v0 offset:2048
	ds_read_b128 v[142:145], v0 offset:3072
	v_add_u32_e32 v0, s53, v157
	ds_read_b128 v[166:169], v0
	ds_read_b128 v[170:173], v0 offset:1024
	ds_read_b128 v[178:181], v0 offset:2048
	ds_read_b128 v[182:185], v0 offset:3072
	v_lshl_add_u64 v[174:175], s[22:23], 0, v[158:159]
	s_add_i32 m0, s34, 0xc000
	ds_read_b128 v[186:189], v176
	ds_read_b128 v[190:193], v176 offset:1024
	ds_read_b128 v[194:197], v176 offset:2048
	ds_read_b128 v[198:201], v176 offset:3072
	ds_read_b128 v[202:205], v176 offset:4096
	ds_read_b128 v[206:209], v176 offset:5120
	ds_read_b128 v[210:213], v176 offset:6144
	ds_read_b128 v[242:245], v176 offset:7168
	global_load_lds_dwordx4 v[174:175], off
	v_lshl_add_u64 v[174:175], s[22:23], 0, v[164:165]
	s_add_i32 m0, s34, 0xe000
	s_nop 0
	global_load_lds_dwordx4 v[174:175], off
	s_waitcnt vmcnt(8)
	s_waitcnt lgkmcnt(0)
	s_barrier
	s_setprio 1
	s_waitcnt lgkmcnt(0)
	v_mfma_f32_16x16x32_bf16 v[130:133], v[126:129], v[186:189], v[130:133]
	v_mfma_f32_16x16x32_bf16 v[122:125], v[138:141], v[186:189], v[122:125]
	v_mfma_f32_16x16x32_bf16 v[110:113], v[126:129], v[194:197], v[110:113]
	v_mfma_f32_16x16x32_bf16 v[106:109], v[138:141], v[194:197], v[106:109]
	v_mfma_f32_16x16x32_bf16 v[94:97], v[126:129], v[202:205], v[94:97]
	v_mfma_f32_16x16x32_bf16 v[90:93], v[138:141], v[202:205], v[90:93]
	v_mfma_f32_16x16x32_bf16 v[78:81], v[126:129], v[210:213], v[78:81]
	v_mfma_f32_16x16x32_bf16 v[74:77], v[138:141], v[210:213], v[74:77]
	v_mfma_f32_16x16x32_bf16 v[130:133], v[134:137], v[190:193], v[130:133]
	v_mfma_f32_16x16x32_bf16 v[122:125], v[142:145], v[190:193], v[122:125]
	v_mfma_f32_16x16x32_bf16 v[110:113], v[134:137], v[198:201], v[110:113]
	v_mfma_f32_16x16x32_bf16 v[106:109], v[142:145], v[198:201], v[106:109]
	v_mfma_f32_16x16x32_bf16 v[94:97], v[134:137], v[206:209], v[94:97]
	v_mfma_f32_16x16x32_bf16 v[90:93], v[142:145], v[206:209], v[90:93]
	v_mfma_f32_16x16x32_bf16 v[78:81], v[134:137], v[242:245], v[78:81]
	v_mfma_f32_16x16x32_bf16 v[74:77], v[142:145], v[242:245], v[74:77]
	s_setprio 0
	s_setprio 1
	v_mfma_f32_16x16x32_bf16 v[118:121], v[166:169], v[186:189], v[118:121]
	v_mfma_f32_16x16x32_bf16 v[114:117], v[178:181], v[186:189], v[114:117]
	v_mfma_f32_16x16x32_bf16 v[102:105], v[166:169], v[194:197], v[102:105]
	v_mfma_f32_16x16x32_bf16 v[98:101], v[178:181], v[194:197], v[98:101]
	v_mfma_f32_16x16x32_bf16 v[86:89], v[166:169], v[202:205], v[86:89]
	v_mfma_f32_16x16x32_bf16 v[82:85], v[178:181], v[202:205], v[82:85]
	v_mfma_f32_16x16x32_bf16 v[70:73], v[166:169], v[210:213], v[70:73]
	v_mfma_f32_16x16x32_bf16 v[66:69], v[178:181], v[210:213], v[66:69]
	v_mfma_f32_16x16x32_bf16 v[118:121], v[170:173], v[190:193], v[118:121]
	v_mfma_f32_16x16x32_bf16 v[114:117], v[182:185], v[190:193], v[114:117]
	v_mfma_f32_16x16x32_bf16 v[102:105], v[170:173], v[198:201], v[102:105]
	v_mfma_f32_16x16x32_bf16 v[98:101], v[182:185], v[198:201], v[98:101]
	v_mfma_f32_16x16x32_bf16 v[86:89], v[170:173], v[206:209], v[86:89]
	v_mfma_f32_16x16x32_bf16 v[82:85], v[182:185], v[206:209], v[82:85]
	v_mfma_f32_16x16x32_bf16 v[70:73], v[170:173], v[242:245], v[70:73]
	v_mfma_f32_16x16x32_bf16 v[66:69], v[182:185], v[242:245], v[66:69]
	s_setprio 0
	s_barrier
	s_add_i32 s52, s52, s31
	v_lshl_add_u64 v[174:175], s[50:51], 0, v[150:151]
	s_mov_b32 m0, s52
	ds_read_b128 v[186:189], v176 offset:16384
	ds_read_b128 v[190:193], v176 offset:17408
	ds_read_b128 v[194:197], v176 offset:18432
	ds_read_b128 v[198:201], v176 offset:19456
	ds_read_b128 v[202:205], v176 offset:20480
	ds_read_b128 v[206:209], v176 offset:21504
	ds_read_b128 v[210:213], v176 offset:22528
	ds_read_b128 v[242:245], v176 offset:23552
	global_load_lds_dwordx4 v[174:175], off
	s_add_i32 m0, s52, 0x2000
	v_lshl_add_u64 v[214:215], s[50:51], 0, v[146:147]
	s_add_u32 s50, s50, s0
	s_addc_u32 s51, s51, 0
	s_add_i32 s52, s53, s31
	global_load_lds_dwordx4 v[214:215], off
	v_lshl_add_u64 v[226:227], s[50:51], 0, v[150:151]
	s_mov_b32 m0, s52
	v_lshl_add_u64 v[228:229], s[50:51], 0, v[146:147]
	global_load_lds_dwordx4 v[226:227], off
	s_add_i32 m0, s52, 0x2000
	v_lshl_add_u64 v[230:231], s[24:25], 0, v[152:153]
	global_load_lds_dwordx4 v[228:229], off
	s_mov_b32 m0, s34
	v_lshl_add_u64 v[232:233], s[24:25], 0, v[148:149]
	global_load_lds_dwordx4 v[230:231], off
	s_mov_b32 m0, s35
	s_nop 0
	global_load_lds_dwordx4 v[232:233], off
	s_waitcnt vmcnt(8)
	s_waitcnt lgkmcnt(0)
	s_barrier
	s_setprio 1
	s_waitcnt lgkmcnt(0)
	v_mfma_f32_16x16x32_bf16 v[62:65], v[126:129], v[186:189], v[62:65]
	v_mfma_f32_16x16x32_bf16 v[58:61], v[138:141], v[186:189], v[58:61]
	v_mfma_f32_16x16x32_bf16 v[46:49], v[126:129], v[194:197], v[46:49]
	v_mfma_f32_16x16x32_bf16 v[42:45], v[138:141], v[194:197], v[42:45]
	v_mfma_f32_16x16x32_bf16 v[30:33], v[126:129], v[202:205], v[30:33]
	v_mfma_f32_16x16x32_bf16 v[26:29], v[138:141], v[202:205], v[26:29]
	v_mfma_f32_16x16x32_bf16 v[14:17], v[126:129], v[210:213], v[14:17]
	v_mfma_f32_16x16x32_bf16 v[10:13], v[138:141], v[210:213], v[10:13]
	v_mfma_f32_16x16x32_bf16 v[62:65], v[134:137], v[190:193], v[62:65]
	v_mfma_f32_16x16x32_bf16 v[58:61], v[142:145], v[190:193], v[58:61]
	v_mfma_f32_16x16x32_bf16 v[46:49], v[134:137], v[198:201], v[46:49]
	v_mfma_f32_16x16x32_bf16 v[42:45], v[142:145], v[198:201], v[42:45]
	v_mfma_f32_16x16x32_bf16 v[30:33], v[134:137], v[206:209], v[30:33]
	v_mfma_f32_16x16x32_bf16 v[26:29], v[142:145], v[206:209], v[26:29]
	v_mfma_f32_16x16x32_bf16 v[14:17], v[134:137], v[242:245], v[14:17]
	v_mfma_f32_16x16x32_bf16 v[10:13], v[142:145], v[242:245], v[10:13]
	s_setprio 0
	s_setprio 1
	v_mfma_f32_16x16x32_bf16 v[54:57], v[166:169], v[186:189], v[54:57]
	v_mfma_f32_16x16x32_bf16 v[50:53], v[178:181], v[186:189], v[50:53]
	v_mfma_f32_16x16x32_bf16 v[38:41], v[166:169], v[194:197], v[38:41]
	v_mfma_f32_16x16x32_bf16 v[34:37], v[178:181], v[194:197], v[34:37]
	v_mfma_f32_16x16x32_bf16 v[22:25], v[166:169], v[202:205], v[22:25]
	v_mfma_f32_16x16x32_bf16 v[18:21], v[178:181], v[202:205], v[18:21]
	v_mfma_f32_16x16x32_bf16 v[6:9], v[166:169], v[210:213], v[6:9]
	v_mfma_f32_16x16x32_bf16 v[2:5], v[178:181], v[210:213], v[2:5]
	v_mfma_f32_16x16x32_bf16 v[54:57], v[170:173], v[190:193], v[54:57]
	v_mfma_f32_16x16x32_bf16 v[50:53], v[182:185], v[190:193], v[50:53]
	v_mfma_f32_16x16x32_bf16 v[38:41], v[170:173], v[198:201], v[38:41]
	v_mfma_f32_16x16x32_bf16 v[34:37], v[182:185], v[198:201], v[34:37]
	v_mfma_f32_16x16x32_bf16 v[22:25], v[170:173], v[206:209], v[22:25]
	v_mfma_f32_16x16x32_bf16 v[18:21], v[182:185], v[206:209], v[18:21]
	v_mfma_f32_16x16x32_bf16 v[6:9], v[170:173], v[242:245], v[6:9]
	v_mfma_f32_16x16x32_bf16 v[2:5], v[182:185], v[242:245], v[2:5]
	s_setprio 0
	s_barrier
	s_add_i32 s50, 0, 0x18000
	v_add_u32_e32 v0, s50, v157
	s_add_i32 s51, 0, 0x1c000
	ds_read_b128 v[126:129], v0
	ds_read_b128 v[134:137], v0 offset:1024
	ds_read_b128 v[138:141], v0 offset:2048
	ds_read_b128 v[142:145], v0 offset:3072
	v_add_u32_e32 v0, s51, v157
	ds_read_b128 v[166:169], v0
	ds_read_b128 v[170:173], v0 offset:1024
	ds_read_b128 v[178:181], v0 offset:2048
	ds_read_b128 v[182:185], v0 offset:3072
	s_add_u32 s24, s24, s0
	s_addc_u32 s25, s25, 0
	s_mov_b32 m0, s36
	v_lshl_add_u64 v[246:247], s[24:25], 0, v[152:153]
	ds_read_b128 v[186:189], v176 offset:32768
	ds_read_b128 v[190:193], v176 offset:33792
	ds_read_b128 v[194:197], v176 offset:34816
	ds_read_b128 v[198:201], v176 offset:35840
	ds_read_b128 v[202:205], v176 offset:36864
	ds_read_b128 v[206:209], v176 offset:37888
	ds_read_b128 v[210:213], v176 offset:38912
	ds_read_b128 v[242:245], v176 offset:39936
	global_load_lds_dwordx4 v[246:247], off
	v_lshl_add_u64 v[246:247], s[24:25], 0, v[148:149]
	s_mov_b32 m0, s37
	s_nop 0
	global_load_lds_dwordx4 v[246:247], off
	s_waitcnt vmcnt(8)
	s_waitcnt lgkmcnt(0)
	s_barrier
	s_setprio 1
	s_waitcnt lgkmcnt(0)
	v_mfma_f32_16x16x32_bf16 v[130:133], v[126:129], v[186:189], v[130:133]
	v_mfma_f32_16x16x32_bf16 v[122:125], v[138:141], v[186:189], v[122:125]
	v_mfma_f32_16x16x32_bf16 v[110:113], v[126:129], v[194:197], v[110:113]
	v_mfma_f32_16x16x32_bf16 v[106:109], v[138:141], v[194:197], v[106:109]
	v_mfma_f32_16x16x32_bf16 v[94:97], v[126:129], v[202:205], v[94:97]
	v_mfma_f32_16x16x32_bf16 v[90:93], v[138:141], v[202:205], v[90:93]
	v_mfma_f32_16x16x32_bf16 v[78:81], v[126:129], v[210:213], v[78:81]
	v_mfma_f32_16x16x32_bf16 v[74:77], v[138:141], v[210:213], v[74:77]
	v_mfma_f32_16x16x32_bf16 v[130:133], v[134:137], v[190:193], v[130:133]
	v_mfma_f32_16x16x32_bf16 v[122:125], v[142:145], v[190:193], v[122:125]
	v_mfma_f32_16x16x32_bf16 v[110:113], v[134:137], v[198:201], v[110:113]
	v_mfma_f32_16x16x32_bf16 v[106:109], v[142:145], v[198:201], v[106:109]
	v_mfma_f32_16x16x32_bf16 v[94:97], v[134:137], v[206:209], v[94:97]
	v_mfma_f32_16x16x32_bf16 v[90:93], v[142:145], v[206:209], v[90:93]
	v_mfma_f32_16x16x32_bf16 v[78:81], v[134:137], v[242:245], v[78:81]
	v_mfma_f32_16x16x32_bf16 v[74:77], v[142:145], v[242:245], v[74:77]
	s_setprio 0
	s_setprio 1
	v_mfma_f32_16x16x32_bf16 v[118:121], v[166:169], v[186:189], v[118:121]
	v_mfma_f32_16x16x32_bf16 v[114:117], v[178:181], v[186:189], v[114:117]
	v_mfma_f32_16x16x32_bf16 v[102:105], v[166:169], v[194:197], v[102:105]
	v_mfma_f32_16x16x32_bf16 v[98:101], v[178:181], v[194:197], v[98:101]
	v_mfma_f32_16x16x32_bf16 v[86:89], v[166:169], v[202:205], v[86:89]
	v_mfma_f32_16x16x32_bf16 v[82:85], v[178:181], v[202:205], v[82:85]
	v_mfma_f32_16x16x32_bf16 v[70:73], v[166:169], v[210:213], v[70:73]
	v_mfma_f32_16x16x32_bf16 v[66:69], v[178:181], v[210:213], v[66:69]
	v_mfma_f32_16x16x32_bf16 v[118:121], v[170:173], v[190:193], v[118:121]
	v_mfma_f32_16x16x32_bf16 v[114:117], v[182:185], v[190:193], v[114:117]
	v_mfma_f32_16x16x32_bf16 v[102:105], v[170:173], v[198:201], v[102:105]
	v_mfma_f32_16x16x32_bf16 v[98:101], v[182:185], v[198:201], v[98:101]
	v_mfma_f32_16x16x32_bf16 v[86:89], v[170:173], v[206:209], v[86:89]
	v_mfma_f32_16x16x32_bf16 v[82:85], v[182:185], v[206:209], v[82:85]
	v_mfma_f32_16x16x32_bf16 v[70:73], v[170:173], v[242:245], v[70:73]
	v_mfma_f32_16x16x32_bf16 v[66:69], v[182:185], v[242:245], v[66:69]
	s_setprio 0
	s_barrier
	s_add_i32 s24, s50, s31
	v_lshl_add_u64 v[174:175], v[174:175], 0, s[94:95]
	s_mov_b32 m0, s24
	ds_read_b128 v[186:189], v176 offset:49152
	ds_read_b128 v[190:193], v176 offset:50176
	ds_read_b128 v[194:197], v176 offset:51200
	ds_read_b128 v[198:201], v176 offset:52224
	ds_read_b128 v[202:205], v176 offset:53248
	ds_read_b128 v[206:209], v176 offset:54272
	ds_read_b128 v[210:213], v176 offset:55296
	ds_read_b128 v[242:245], v176 offset:56320
	global_load_lds_dwordx4 v[174:175], off
	v_lshl_add_u64 v[174:175], v[214:215], 0, s[94:95]
	s_add_i32 m0, s24, 0x2000
	s_add_i32 s24, s51, s31
	global_load_lds_dwordx4 v[174:175], off
	v_lshl_add_u64 v[174:175], v[226:227], 0, s[94:95]
	s_mov_b32 m0, s24
	s_nop 0
	global_load_lds_dwordx4 v[174:175], off
	v_lshl_add_u64 v[174:175], v[228:229], 0, s[94:95]
	s_add_i32 m0, s24, 0x2000
	s_nop 0
	global_load_lds_dwordx4 v[174:175], off
	v_lshl_add_u64 v[174:175], v[230:231], 0, s[94:95]
	s_mov_b32 m0, s38
	s_nop 0
	global_load_lds_dwordx4 v[174:175], off
	v_lshl_add_u64 v[174:175], v[232:233], 0, s[94:95]
	s_mov_b32 m0, s39
	s_nop 0
	global_load_lds_dwordx4 v[174:175], off
	s_waitcnt vmcnt(8)
	s_waitcnt lgkmcnt(0)
	s_barrier
	s_setprio 1
	s_waitcnt lgkmcnt(0)
	v_mfma_f32_16x16x32_bf16 v[62:65], v[126:129], v[186:189], v[62:65]
	v_mfma_f32_16x16x32_bf16 v[58:61], v[138:141], v[186:189], v[58:61]
	v_mfma_f32_16x16x32_bf16 v[46:49], v[126:129], v[194:197], v[46:49]
	v_mfma_f32_16x16x32_bf16 v[42:45], v[138:141], v[194:197], v[42:45]
	v_mfma_f32_16x16x32_bf16 v[30:33], v[126:129], v[202:205], v[30:33]
	v_mfma_f32_16x16x32_bf16 v[26:29], v[138:141], v[202:205], v[26:29]
	v_mfma_f32_16x16x32_bf16 v[14:17], v[126:129], v[210:213], v[14:17]
	v_mfma_f32_16x16x32_bf16 v[10:13], v[138:141], v[210:213], v[10:13]
	v_mfma_f32_16x16x32_bf16 v[62:65], v[134:137], v[190:193], v[62:65]
	v_mfma_f32_16x16x32_bf16 v[58:61], v[142:145], v[190:193], v[58:61]
	v_mfma_f32_16x16x32_bf16 v[46:49], v[134:137], v[198:201], v[46:49]
	v_mfma_f32_16x16x32_bf16 v[42:45], v[142:145], v[198:201], v[42:45]
	v_mfma_f32_16x16x32_bf16 v[30:33], v[134:137], v[206:209], v[30:33]
	v_mfma_f32_16x16x32_bf16 v[26:29], v[142:145], v[206:209], v[26:29]
	v_mfma_f32_16x16x32_bf16 v[14:17], v[134:137], v[242:245], v[14:17]
	v_mfma_f32_16x16x32_bf16 v[10:13], v[142:145], v[242:245], v[10:13]
	s_setprio 0
	s_setprio 1
	v_mfma_f32_16x16x32_bf16 v[54:57], v[166:169], v[186:189], v[54:57]
	v_mfma_f32_16x16x32_bf16 v[50:53], v[178:181], v[186:189], v[50:53]
	v_mfma_f32_16x16x32_bf16 v[38:41], v[166:169], v[194:197], v[38:41]
	v_mfma_f32_16x16x32_bf16 v[34:37], v[178:181], v[194:197], v[34:37]
	v_mfma_f32_16x16x32_bf16 v[22:25], v[166:169], v[202:205], v[22:25]
	v_mfma_f32_16x16x32_bf16 v[18:21], v[178:181], v[202:205], v[18:21]
	v_mfma_f32_16x16x32_bf16 v[6:9], v[166:169], v[210:213], v[6:9]
	v_mfma_f32_16x16x32_bf16 v[2:5], v[178:181], v[210:213], v[2:5]
	v_mfma_f32_16x16x32_bf16 v[54:57], v[170:173], v[190:193], v[54:57]
	v_mfma_f32_16x16x32_bf16 v[50:53], v[182:185], v[190:193], v[50:53]
	v_mfma_f32_16x16x32_bf16 v[38:41], v[170:173], v[198:201], v[38:41]
	v_mfma_f32_16x16x32_bf16 v[34:37], v[182:185], v[198:201], v[34:37]
	v_mfma_f32_16x16x32_bf16 v[22:25], v[170:173], v[206:209], v[22:25]
	v_mfma_f32_16x16x32_bf16 v[18:21], v[182:185], v[206:209], v[18:21]
	v_mfma_f32_16x16x32_bf16 v[6:9], v[170:173], v[242:245], v[6:9]
	v_mfma_f32_16x16x32_bf16 v[2:5], v[182:185], v[242:245], v[2:5]
	s_add_u32 s22, s22, 0x100
	s_addc_u32 s23, s23, 0
	s_add_u32 s47, s47, 0x100
	s_addc_u32 s48, s48, 0
	s_cmp_ge_u32 s49, s40
	s_mov_b32 s24, s49
	s_setprio 0
	s_barrier
	s_cbranch_scc0 .LBB0_233
	s_and_b64 vcc, exec, s[12:13]
	s_cbranch_vccz .LBB0_236
	s_barrier

.LBB0_402:
	s_add_i32 s53, s8, 2
	s_add_u32 s54, s0, 0xfffc0080
	s_addc_u32 s9, s1, -1
	s_add_i32 s56, 0, 0x10000
	s_cmp_eq_u32 s47, s8
	s_cselect_b32 s9, s27, s9
	s_cselect_b32 s8, s52, s54
	v_add_u32_e32 v0, s56, v141
	s_cselect_b32 s55, s29, s35
	s_cselect_b32 s54, s28, s34
	s_add_i32 s57, 0, 0x14000
	ds_read_b128 v[148:151], v0
	ds_read_b128 v[152:155], v0 offset:1024
	ds_read_b128 v[156:159], v0 offset:2048
	ds_read_b128 v[164:167], v0 offset:3072
	v_add_u32_e32 v0, s57, v141
	ds_read_b128 v[168:171], v0
	ds_read_b128 v[172:175], v0 offset:1024
	ds_read_b128 v[176:179], v0 offset:2048
	ds_read_b128 v[180:183], v0 offset:3072
	v_lshl_add_u64 v[226:227], s[0:1], 0, v[142:143]
	s_add_i32 m0, s40, 0xc000
	ds_read_b128 v[184:187], v147
	ds_read_b128 v[188:191], v147 offset:1024
	ds_read_b128 v[192:195], v147 offset:2048
	ds_read_b128 v[196:199], v147 offset:3072
	ds_read_b128 v[200:203], v147 offset:4096
	ds_read_b128 v[204:207], v147 offset:5120
	ds_read_b128 v[208:211], v147 offset:6144
	ds_read_b128 v[212:215], v147 offset:7168
	global_load_lds_dwordx4 v[226:227], off
	v_lshl_add_u64 v[226:227], s[0:1], 0, v[144:145]
	s_add_i32 m0, s40, 0xe000
	s_nop 0
	global_load_lds_dwordx4 v[226:227], off
	s_waitcnt vmcnt(8)
	s_waitcnt lgkmcnt(0)
	s_barrier
	s_setprio 1
	s_waitcnt lgkmcnt(0)
	v_mfma_f32_16x16x32_bf16 v[126:129], v[148:151], v[184:187], v[126:129]
	v_mfma_f32_16x16x32_bf16 v[122:125], v[156:159], v[184:187], v[122:125]
	v_mfma_f32_16x16x32_bf16 v[110:113], v[148:151], v[192:195], v[110:113]
	v_mfma_f32_16x16x32_bf16 v[106:109], v[156:159], v[192:195], v[106:109]
	v_mfma_f32_16x16x32_bf16 v[94:97], v[148:151], v[200:203], v[94:97]
	v_mfma_f32_16x16x32_bf16 v[90:93], v[156:159], v[200:203], v[90:93]
	v_mfma_f32_16x16x32_bf16 v[78:81], v[148:151], v[208:211], v[78:81]
	v_mfma_f32_16x16x32_bf16 v[74:77], v[156:159], v[208:211], v[74:77]
	v_mfma_f32_16x16x32_bf16 v[126:129], v[152:155], v[188:191], v[126:129]
	v_mfma_f32_16x16x32_bf16 v[122:125], v[164:167], v[188:191], v[122:125]
	v_mfma_f32_16x16x32_bf16 v[110:113], v[152:155], v[196:199], v[110:113]
	v_mfma_f32_16x16x32_bf16 v[106:109], v[164:167], v[196:199], v[106:109]
	v_mfma_f32_16x16x32_bf16 v[94:97], v[152:155], v[204:207], v[94:97]
	v_mfma_f32_16x16x32_bf16 v[90:93], v[164:167], v[204:207], v[90:93]
	v_mfma_f32_16x16x32_bf16 v[78:81], v[152:155], v[212:215], v[78:81]
	v_mfma_f32_16x16x32_bf16 v[74:77], v[164:167], v[212:215], v[74:77]
	s_setprio 0
	s_setprio 1
	v_mfma_f32_16x16x32_bf16 v[118:121], v[168:171], v[184:187], v[118:121]
	v_mfma_f32_16x16x32_bf16 v[114:117], v[176:179], v[184:187], v[114:117]
	v_mfma_f32_16x16x32_bf16 v[102:105], v[168:171], v[192:195], v[102:105]
	v_mfma_f32_16x16x32_bf16 v[98:101], v[176:179], v[192:195], v[98:101]
	v_mfma_f32_16x16x32_bf16 v[86:89], v[168:171], v[200:203], v[86:89]
	v_mfma_f32_16x16x32_bf16 v[82:85], v[176:179], v[200:203], v[82:85]
	v_mfma_f32_16x16x32_bf16 v[70:73], v[168:171], v[208:211], v[70:73]
	v_mfma_f32_16x16x32_bf16 v[66:69], v[176:179], v[208:211], v[66:69]
	v_mfma_f32_16x16x32_bf16 v[118:121], v[172:175], v[188:191], v[118:121]
	v_mfma_f32_16x16x32_bf16 v[114:117], v[180:183], v[188:191], v[114:117]
	v_mfma_f32_16x16x32_bf16 v[102:105], v[172:175], v[196:199], v[102:105]
	v_mfma_f32_16x16x32_bf16 v[98:101], v[180:183], v[196:199], v[98:101]
	v_mfma_f32_16x16x32_bf16 v[86:89], v[172:175], v[204:207], v[86:89]
	v_mfma_f32_16x16x32_bf16 v[82:85], v[180:183], v[204:207], v[82:85]
	v_mfma_f32_16x16x32_bf16 v[70:73], v[172:175], v[212:215], v[70:73]
	v_mfma_f32_16x16x32_bf16 v[66:69], v[180:183], v[212:215], v[66:69]
	s_setprio 0
	s_barrier
	s_add_i32 s56, s56, s39
	v_lshl_add_u64 v[226:227], s[54:55], 0, v[134:135]
	s_mov_b32 m0, s56
	ds_read_b128 v[184:187], v147 offset:16384
	ds_read_b128 v[188:191], v147 offset:17408
	ds_read_b128 v[192:195], v147 offset:18432
	ds_read_b128 v[196:199], v147 offset:19456
	ds_read_b128 v[200:203], v147 offset:20480
	ds_read_b128 v[204:207], v147 offset:21504
	ds_read_b128 v[208:211], v147 offset:22528
	ds_read_b128 v[212:215], v147 offset:23552
	global_load_lds_dwordx4 v[226:227], off
	s_add_i32 m0, s56, 0x2000
	v_lshl_add_u64 v[228:229], s[54:55], 0, v[130:131]
	s_add_u32 s54, s54, s37
	s_addc_u32 s55, s55, 0
	s_add_i32 s56, s57, s39
	global_load_lds_dwordx4 v[228:229], off
	v_lshl_add_u64 v[230:231], s[54:55], 0, v[134:135]
	s_mov_b32 m0, s56
	v_lshl_add_u64 v[242:243], s[54:55], 0, v[130:131]
	global_load_lds_dwordx4 v[230:231], off
	s_add_i32 m0, s56, 0x2000
	v_lshl_add_u64 v[244:245], s[8:9], 0, v[136:137]
	global_load_lds_dwordx4 v[242:243], off
	s_mov_b32 m0, s40
	v_lshl_add_u64 v[246:247], s[8:9], 0, v[132:133]
	global_load_lds_dwordx4 v[244:245], off
	s_mov_b32 m0, s41
	s_nop 0
	global_load_lds_dwordx4 v[246:247], off
	s_waitcnt vmcnt(8)
	s_waitcnt lgkmcnt(0)
	s_barrier
	s_setprio 1
	s_waitcnt lgkmcnt(0)
	v_mfma_f32_16x16x32_bf16 v[62:65], v[148:151], v[184:187], v[62:65]
	v_mfma_f32_16x16x32_bf16 v[58:61], v[156:159], v[184:187], v[58:61]
	v_mfma_f32_16x16x32_bf16 v[46:49], v[148:151], v[192:195], v[46:49]
	v_mfma_f32_16x16x32_bf16 v[42:45], v[156:159], v[192:195], v[42:45]
	v_mfma_f32_16x16x32_bf16 v[30:33], v[148:151], v[200:203], v[30:33]
	v_mfma_f32_16x16x32_bf16 v[26:29], v[156:159], v[200:203], v[26:29]
	v_mfma_f32_16x16x32_bf16 v[14:17], v[148:151], v[208:211], v[14:17]
	v_mfma_f32_16x16x32_bf16 v[10:13], v[156:159], v[208:211], v[10:13]
	v_mfma_f32_16x16x32_bf16 v[62:65], v[152:155], v[188:191], v[62:65]
	v_mfma_f32_16x16x32_bf16 v[58:61], v[164:167], v[188:191], v[58:61]
	v_mfma_f32_16x16x32_bf16 v[46:49], v[152:155], v[196:199], v[46:49]
	v_mfma_f32_16x16x32_bf16 v[42:45], v[164:167], v[196:199], v[42:45]
	v_mfma_f32_16x16x32_bf16 v[30:33], v[152:155], v[204:207], v[30:33]
	v_mfma_f32_16x16x32_bf16 v[26:29], v[164:167], v[204:207], v[26:29]
	v_mfma_f32_16x16x32_bf16 v[14:17], v[152:155], v[212:215], v[14:17]
	v_mfma_f32_16x16x32_bf16 v[10:13], v[164:167], v[212:215], v[10:13]
	s_setprio 0
	s_setprio 1
	v_mfma_f32_16x16x32_bf16 v[54:57], v[168:171], v[184:187], v[54:57]
	v_mfma_f32_16x16x32_bf16 v[50:53], v[176:179], v[184:187], v[50:53]
	v_mfma_f32_16x16x32_bf16 v[38:41], v[168:171], v[192:195], v[38:41]
	v_mfma_f32_16x16x32_bf16 v[34:37], v[176:179], v[192:195], v[34:37]
	v_mfma_f32_16x16x32_bf16 v[22:25], v[168:171], v[200:203], v[22:25]
	v_mfma_f32_16x16x32_bf16 v[18:21], v[176:179], v[200:203], v[18:21]
	v_mfma_f32_16x16x32_bf16 v[6:9], v[168:171], v[208:211], v[6:9]
	v_mfma_f32_16x16x32_bf16 v[2:5], v[176:179], v[208:211], v[2:5]
	v_mfma_f32_16x16x32_bf16 v[54:57], v[172:175], v[188:191], v[54:57]
	v_mfma_f32_16x16x32_bf16 v[50:53], v[180:183], v[188:191], v[50:53]
	v_mfma_f32_16x16x32_bf16 v[38:41], v[172:175], v[196:199], v[38:41]
	v_mfma_f32_16x16x32_bf16 v[34:37], v[180:183], v[196:199], v[34:37]
	v_mfma_f32_16x16x32_bf16 v[22:25], v[172:175], v[204:207], v[22:25]
	v_mfma_f32_16x16x32_bf16 v[18:21], v[180:183], v[204:207], v[18:21]
	v_mfma_f32_16x16x32_bf16 v[6:9], v[172:175], v[212:215], v[6:9]
	v_mfma_f32_16x16x32_bf16 v[2:5], v[180:183], v[212:215], v[2:5]
	s_setprio 0
	s_barrier
	s_add_i32 s54, 0, 0x18000
	v_add_u32_e32 v0, s54, v141
	s_add_i32 s55, 0, 0x1c000
	ds_read_b128 v[148:151], v0
	ds_read_b128 v[152:155], v0 offset:1024
	ds_read_b128 v[156:159], v0 offset:2048
	ds_read_b128 v[164:167], v0 offset:3072
	v_add_u32_e32 v0, s55, v141
	ds_read_b128 v[168:171], v0
	ds_read_b128 v[172:175], v0 offset:1024
	ds_read_b128 v[176:179], v0 offset:2048
	ds_read_b128 v[180:183], v0 offset:3072
	s_add_u32 s8, s8, 0x40000
	s_addc_u32 s9, s9, 0
	s_mov_b32 m0, s42
	v_lshl_add_u64 v[232:233], s[8:9], 0, v[136:137]
	ds_read_b128 v[184:187], v147 offset:32768
	ds_read_b128 v[188:191], v147 offset:33792
	ds_read_b128 v[192:195], v147 offset:34816
	ds_read_b128 v[196:199], v147 offset:35840
	ds_read_b128 v[200:203], v147 offset:36864
	ds_read_b128 v[204:207], v147 offset:37888
	ds_read_b128 v[208:211], v147 offset:38912
	ds_read_b128 v[212:215], v147 offset:39936
	global_load_lds_dwordx4 v[232:233], off
	v_lshl_add_u64 v[232:233], s[8:9], 0, v[132:133]
	s_mov_b32 m0, s43
	s_nop 0
	global_load_lds_dwordx4 v[232:233], off
	s_waitcnt vmcnt(8)
	s_waitcnt lgkmcnt(0)
	s_barrier
	s_setprio 1
	s_waitcnt lgkmcnt(0)
	v_mfma_f32_16x16x32_bf16 v[126:129], v[148:151], v[184:187], v[126:129]
	v_mfma_f32_16x16x32_bf16 v[122:125], v[156:159], v[184:187], v[122:125]
	v_mfma_f32_16x16x32_bf16 v[110:113], v[148:151], v[192:195], v[110:113]
	v_mfma_f32_16x16x32_bf16 v[106:109], v[156:159], v[192:195], v[106:109]
	v_mfma_f32_16x16x32_bf16 v[94:97], v[148:151], v[200:203], v[94:97]
	v_mfma_f32_16x16x32_bf16 v[90:93], v[156:159], v[200:203], v[90:93]
	v_mfma_f32_16x16x32_bf16 v[78:81], v[148:151], v[208:211], v[78:81]
	v_mfma_f32_16x16x32_bf16 v[74:77], v[156:159], v[208:211], v[74:77]
	v_mfma_f32_16x16x32_bf16 v[126:129], v[152:155], v[188:191], v[126:129]
	v_mfma_f32_16x16x32_bf16 v[122:125], v[164:167], v[188:191], v[122:125]
	v_mfma_f32_16x16x32_bf16 v[110:113], v[152:155], v[196:199], v[110:113]
	v_mfma_f32_16x16x32_bf16 v[106:109], v[164:167], v[196:199], v[106:109]
	v_mfma_f32_16x16x32_bf16 v[94:97], v[152:155], v[204:207], v[94:97]
	v_mfma_f32_16x16x32_bf16 v[90:93], v[164:167], v[204:207], v[90:93]
	v_mfma_f32_16x16x32_bf16 v[78:81], v[152:155], v[212:215], v[78:81]
	v_mfma_f32_16x16x32_bf16 v[74:77], v[164:167], v[212:215], v[74:77]
	s_setprio 0
	s_setprio 1
	v_mfma_f32_16x16x32_bf16 v[118:121], v[168:171], v[184:187], v[118:121]
	v_mfma_f32_16x16x32_bf16 v[114:117], v[176:179], v[184:187], v[114:117]
	v_mfma_f32_16x16x32_bf16 v[102:105], v[168:171], v[192:195], v[102:105]
	v_mfma_f32_16x16x32_bf16 v[98:101], v[176:179], v[192:195], v[98:101]
	v_mfma_f32_16x16x32_bf16 v[86:89], v[168:171], v[200:203], v[86:89]
	v_mfma_f32_16x16x32_bf16 v[82:85], v[176:179], v[200:203], v[82:85]
	v_mfma_f32_16x16x32_bf16 v[70:73], v[168:171], v[208:211], v[70:73]
	v_mfma_f32_16x16x32_bf16 v[66:69], v[176:179], v[208:211], v[66:69]
	v_mfma_f32_16x16x32_bf16 v[118:121], v[172:175], v[188:191], v[118:121]
	v_mfma_f32_16x16x32_bf16 v[114:117], v[180:183], v[188:191], v[114:117]
	v_mfma_f32_16x16x32_bf16 v[102:105], v[172:175], v[196:199], v[102:105]
	v_mfma_f32_16x16x32_bf16 v[98:101], v[180:183], v[196:199], v[98:101]
	v_mfma_f32_16x16x32_bf16 v[86:89], v[172:175], v[204:207], v[86:89]
	v_mfma_f32_16x16x32_bf16 v[82:85], v[180:183], v[204:207], v[82:85]
	v_mfma_f32_16x16x32_bf16 v[70:73], v[172:175], v[212:215], v[70:73]
	v_mfma_f32_16x16x32_bf16 v[66:69], v[180:183], v[212:215], v[66:69]
	s_setprio 0
	s_barrier
	s_add_i32 s8, s54, s39
	v_lshl_add_u64 v[226:227], v[226:227], 0, s[94:95]
	s_mov_b32 m0, s8
	ds_read_b128 v[184:187], v147 offset:49152
	ds_read_b128 v[188:191], v147 offset:50176
	ds_read_b128 v[192:195], v147 offset:51200
	ds_read_b128 v[196:199], v147 offset:52224
	ds_read_b128 v[200:203], v147 offset:53248
	ds_read_b128 v[204:207], v147 offset:54272
	ds_read_b128 v[208:211], v147 offset:55296
	ds_read_b128 v[212:215], v147 offset:56320
	global_load_lds_dwordx4 v[226:227], off
	v_lshl_add_u64 v[226:227], v[228:229], 0, s[94:95]
	s_add_i32 m0, s8, 0x2000
	s_add_i32 s8, s55, s39
	global_load_lds_dwordx4 v[226:227], off
	v_lshl_add_u64 v[226:227], v[230:231], 0, s[94:95]
	s_mov_b32 m0, s8
	s_nop 0
	global_load_lds_dwordx4 v[226:227], off
	v_lshl_add_u64 v[226:227], v[242:243], 0, s[94:95]
	s_add_i32 m0, s8, 0x2000
	s_nop 0
	global_load_lds_dwordx4 v[226:227], off
	v_lshl_add_u64 v[226:227], v[244:245], 0, s[94:95]
	s_mov_b32 m0, s44
	s_nop 0
	global_load_lds_dwordx4 v[226:227], off
	v_lshl_add_u64 v[226:227], v[246:247], 0, s[94:95]
	s_mov_b32 m0, s45
	s_nop 0
	global_load_lds_dwordx4 v[226:227], off
	s_waitcnt vmcnt(8)
	s_waitcnt lgkmcnt(0)
	s_barrier
	s_setprio 1
	s_waitcnt lgkmcnt(0)
	v_mfma_f32_16x16x32_bf16 v[62:65], v[148:151], v[184:187], v[62:65]
	v_mfma_f32_16x16x32_bf16 v[58:61], v[156:159], v[184:187], v[58:61]
	v_mfma_f32_16x16x32_bf16 v[46:49], v[148:151], v[192:195], v[46:49]
	v_mfma_f32_16x16x32_bf16 v[42:45], v[156:159], v[192:195], v[42:45]
	v_mfma_f32_16x16x32_bf16 v[30:33], v[148:151], v[200:203], v[30:33]
	v_mfma_f32_16x16x32_bf16 v[26:29], v[156:159], v[200:203], v[26:29]
	v_mfma_f32_16x16x32_bf16 v[14:17], v[148:151], v[208:211], v[14:17]
	v_mfma_f32_16x16x32_bf16 v[10:13], v[156:159], v[208:211], v[10:13]
	v_mfma_f32_16x16x32_bf16 v[62:65], v[152:155], v[188:191], v[62:65]
	v_mfma_f32_16x16x32_bf16 v[58:61], v[164:167], v[188:191], v[58:61]
	v_mfma_f32_16x16x32_bf16 v[46:49], v[152:155], v[196:199], v[46:49]
	v_mfma_f32_16x16x32_bf16 v[42:45], v[164:167], v[196:199], v[42:45]
	v_mfma_f32_16x16x32_bf16 v[30:33], v[152:155], v[204:207], v[30:33]
	v_mfma_f32_16x16x32_bf16 v[26:29], v[164:167], v[204:207], v[26:29]
	v_mfma_f32_16x16x32_bf16 v[14:17], v[152:155], v[212:215], v[14:17]
	v_mfma_f32_16x16x32_bf16 v[10:13], v[164:167], v[212:215], v[10:13]
	s_setprio 0
	s_setprio 1
	v_mfma_f32_16x16x32_bf16 v[54:57], v[168:171], v[184:187], v[54:57]
	v_mfma_f32_16x16x32_bf16 v[50:53], v[176:179], v[184:187], v[50:53]
	v_mfma_f32_16x16x32_bf16 v[38:41], v[168:171], v[192:195], v[38:41]
	v_mfma_f32_16x16x32_bf16 v[34:37], v[176:179], v[192:195], v[34:37]
	v_mfma_f32_16x16x32_bf16 v[22:25], v[168:171], v[200:203], v[22:25]
	v_mfma_f32_16x16x32_bf16 v[18:21], v[176:179], v[200:203], v[18:21]
	v_mfma_f32_16x16x32_bf16 v[6:9], v[168:171], v[208:211], v[6:9]
	v_mfma_f32_16x16x32_bf16 v[2:5], v[176:179], v[208:211], v[2:5]
	v_mfma_f32_16x16x32_bf16 v[54:57], v[172:175], v[188:191], v[54:57]
	v_mfma_f32_16x16x32_bf16 v[50:53], v[180:183], v[188:191], v[50:53]
	v_mfma_f32_16x16x32_bf16 v[38:41], v[172:175], v[196:199], v[38:41]
	v_mfma_f32_16x16x32_bf16 v[34:37], v[180:183], v[196:199], v[34:37]
	v_mfma_f32_16x16x32_bf16 v[22:25], v[172:175], v[204:207], v[22:25]
	v_mfma_f32_16x16x32_bf16 v[18:21], v[180:183], v[204:207], v[18:21]
	v_mfma_f32_16x16x32_bf16 v[6:9], v[172:175], v[212:215], v[6:9]
	v_mfma_f32_16x16x32_bf16 v[2:5], v[180:183], v[212:215], v[2:5]
	s_add_u32 s0, s0, 0x100
	s_addc_u32 s1, s1, 0
	s_add_u32 s34, s34, 0x100
	s_addc_u32 s35, s35, 0
	s_cmp_ge_u32 s53, s5
	s_mov_b32 s8, s53
	s_setprio 0
	s_barrier
	s_cbranch_scc0 .LBB0_402
	s_and_b64 vcc, exec, s[20:21]
	s_cbranch_vccz .LBB0_405
	s_barrier
